# mix_pre (sample sequences): stage-1 loop's 16 serialized load trips issued as one batch; stage-5 per-row operand loads (20 serialized trips) prefetched at the top of the body into otherwise unused reg
# speedup vs baseline: 1.0074x; 1.0061x over previous
.LBB0_1041:
	s_barrier
	s_lshl_b32 s100, s64, 2
	s_add_i32 s100, s100, 0x2040
	s_mul_hi_i32 s101, s100, 0x3000
	s_mul_i32 s100, s100, 0x3000
	s_add_u32 s100, s56, s100
	s_addc_u32 s101, s57, s101
	v_lshl_add_u64 v[140:141], v[106:107], 1, s[100:101]
	s_mov_b64 s[98:99], 0x1800
	v_lshl_add_u64 v[140:141], v[140:141], 0, s[98:99]
	s_mov_b64 s[98:99], 0x3000
	v_mov_b32_e32 v142, 0x2000
	global_load_ushort v137, v[140:141], off offset:-1536
	global_load_ushort v214, v[140:141], off offset:-512
	global_load_ushort v233, v[140:141], off offset:2560
	global_load_dwordx4 v[178:181], v142, s[100:101] offset:2560
	global_load_dwordx4 v[194:197], v142, s[100:101] offset:2576
	v_lshl_add_u64 v[140:141], v[140:141], 0, s[98:99]
	v_mov_b32_e32 v142, 0x5000
	global_load_ushort v234, v[140:141], off offset:-1536
	global_load_ushort v235, v[140:141], off offset:-512
	global_load_ushort v236, v[140:141], off offset:2560
	global_load_dwordx4 v[198:201], v142, s[100:101] offset:2560
	global_load_dwordx4 v[202:205], v142, s[100:101] offset:2576
	v_lshl_add_u64 v[140:141], v[140:141], 0, s[98:99]
	v_mov_b32_e32 v142, 0x8000
	global_load_ushort v244, v[140:141], off offset:-1536
	global_load_ushort v245, v[140:141], off offset:-512
	global_load_ushort v238, v[140:141], off offset:2560
	global_load_dwordx4 v[206:209], v142, s[100:101] offset:2560
	global_load_dwordx4 v[210:213], v142, s[100:101] offset:2576
	v_lshl_add_u64 v[140:141], v[140:141], 0, s[98:99]
	v_mov_b32_e32 v142, 0xb000
	global_load_ushort v239, v[140:141], off offset:-1536
	global_load_ushort v240, v[140:141], off offset:-512
	global_load_ushort v241, v[140:141], off offset:2560
	global_load_dwordx4 v[222:225], v142, s[100:101] offset:2560
	global_load_dwordx4 v[226:229], v142, s[100:101] offset:2576
	s_and_saveexec_b64 s[12:13], s[0:1]
	s_cbranch_execz .LBB0_1044
	v_mov_b32_e32 v66, 0x1c00
	v_mad_i64_i32 v[0:1], s[22:23], s62, v232, v[50:51]
	v_mad_i64_i32 v[2:3], s[22:23], s64, v66, v[52:53]
	v_mad_i64_i32 v[66:67], s[22:23], s64, v66, v[18:19]
	s_mov_b64 s[22:23], 0
	v_mov_b64_e32 v[68:69], v[48:49]
	v_mov_b32_e32 v70, v89
	v_mov_b32_e32 v71, v88
.LBB0_1043:
	s_mov_b64 s[98:99], 0x3000
	v_lshl_add_u64 v[72:73], v[0:1], 0, s[98:99]
	s_mov_b64 s[98:99], 0x6000
	v_lshl_add_u64 v[74:75], v[0:1], 0, s[98:99]
	s_mov_b64 s[98:99], 0x9000
	v_lshl_add_u64 v[76:77], v[0:1], 0, s[98:99]
	s_mov_b64 s[98:99], 0x1000
	v_lshl_add_u64 v[98:99], v[2:3], 0, s[98:99]
	v_lshl_add_u64 v[100:101], v[68:69], 0, s[98:99]
	v_lshl_add_u64 v[102:103], v[66:67], 0, s[98:99]
	v_add_u32_e32 v104, 0x200, v71
	v_add_u32_e32 v105, 0x400, v71
	v_add_u32_e32 v96, 0x600, v71
	v_cmp_ge_i32_e64 s[24:25], s70, v104
	v_cmp_ge_i32_e64 s[26:27], s70, v105
	v_cmp_ge_i32_e64 s[30:31], s70, v96
	s_mov_b64 s[22:23], exec
	global_load_dword v108, v[2:3], off
	global_load_dword v109, v[68:69], off
	global_load_ushort v110, v[0:1], off
	global_load_ushort v111, v[72:73], off
	global_load_ushort v112, v[74:75], off
	global_load_ushort v113, v[76:77], off
	s_and_b64 exec, s[22:23], s[24:25]
	global_load_dword v114, v[2:3], off offset:2048
	global_load_dword v115, v[68:69], off offset:2048
	global_load_ushort v116, v[0:1], off offset:1024
	global_load_ushort v117, v[72:73], off offset:1024
	global_load_ushort v118, v[74:75], off offset:1024
	global_load_ushort v119, v[76:77], off offset:1024
	s_and_b64 exec, s[22:23], s[26:27]
	global_load_dword v120, v[98:99], off
	global_load_dword v121, v[100:101], off
	global_load_ushort v122, v[0:1], off offset:2048
	global_load_ushort v123, v[72:73], off offset:2048
	global_load_ushort v124, v[74:75], off offset:2048
	global_load_ushort v125, v[76:77], off offset:2048
	s_and_b64 exec, s[22:23], s[30:31]
	global_load_dword v126, v[98:99], off offset:2048
	global_load_dword v127, v[100:101], off offset:2048
	global_load_ushort v128, v[0:1], off offset:3072
	global_load_ushort v129, v[72:73], off offset:3072
	global_load_ushort v130, v[74:75], off offset:3072
	global_load_ushort v131, v[76:77], off offset:3072
	s_mov_b64 exec, s[22:23]
	s_waitcnt vmcnt(0)
	v_lshlrev_b32_e32 v110, 16, v110
	v_lshlrev_b32_e32 v111, 16, v111
	v_lshlrev_b32_e32 v112, 16, v112
	v_lshlrev_b32_e32 v113, 16, v113
	v_sub_f32_e32 v132, v108, v110
	v_sub_f32_e32 v133, v110, v111
	v_fmac_f32_e32 v110, v109, v132
	v_fma_f32 v134, v109, v133, v111
	ds_write2st64_b32 v70, v110, v134 offset1:28
	v_sub_f32_e32 v132, v111, v112
	v_sub_f32_e32 v133, v112, v113
	v_fmac_f32_e32 v112, v109, v132
	v_fma_f32 v135, v109, v133, v113
	ds_write2st64_b32 v70, v112, v135 offset0:56 offset1:84
	global_store_dword v[66:67], v113, off
	s_and_b64 exec, s[22:23], s[24:25]
	v_lshlrev_b32_e32 v116, 16, v116
	v_lshlrev_b32_e32 v117, 16, v117
	v_lshlrev_b32_e32 v118, 16, v118
	v_lshlrev_b32_e32 v119, 16, v119
	v_sub_f32_e32 v132, v114, v116
	v_sub_f32_e32 v133, v116, v117
	v_fmac_f32_e32 v116, v115, v132
	v_fma_f32 v134, v115, v133, v117
	ds_write2st64_b32 v70, v116, v134 offset0:8 offset1:36
	v_sub_f32_e32 v132, v117, v118
	v_sub_f32_e32 v133, v118, v119
	v_fmac_f32_e32 v118, v115, v132
	v_fma_f32 v135, v115, v133, v119
	ds_write2st64_b32 v70, v118, v135 offset0:64 offset1:92
	global_store_dword v[66:67], v119, off offset:2048
	s_and_b64 exec, s[22:23], s[26:27]
	v_lshlrev_b32_e32 v122, 16, v122
	v_lshlrev_b32_e32 v123, 16, v123
	v_lshlrev_b32_e32 v124, 16, v124
	v_lshlrev_b32_e32 v125, 16, v125
	v_sub_f32_e32 v132, v120, v122
	v_sub_f32_e32 v133, v122, v123
	v_fmac_f32_e32 v122, v121, v132
	v_fma_f32 v134, v121, v133, v123
	ds_write2st64_b32 v70, v122, v134 offset0:16 offset1:44
	v_sub_f32_e32 v132, v123, v124
	v_sub_f32_e32 v133, v124, v125
	v_fmac_f32_e32 v124, v121, v132
	v_fma_f32 v135, v121, v133, v125
	ds_write2st64_b32 v70, v124, v135 offset0:72 offset1:100
	global_store_dword v[102:103], v125, off
	s_and_b64 exec, s[22:23], s[30:31]
	v_lshlrev_b32_e32 v128, 16, v128
	v_lshlrev_b32_e32 v129, 16, v129
	v_lshlrev_b32_e32 v130, 16, v130
	v_lshlrev_b32_e32 v131, 16, v131
	v_sub_f32_e32 v132, v126, v128
	v_sub_f32_e32 v133, v128, v129
	v_fmac_f32_e32 v128, v127, v132
	v_fma_f32 v134, v127, v133, v129
	ds_write2st64_b32 v70, v128, v134 offset0:24 offset1:52
	v_sub_f32_e32 v132, v129, v130
	v_sub_f32_e32 v133, v130, v131
	v_fmac_f32_e32 v130, v127, v132
	v_fma_f32 v135, v127, v133, v131
	ds_write2st64_b32 v70, v130, v135 offset0:80 offset1:108
	global_store_dword v[102:103], v131, off offset:2048
	s_mov_b64 exec, s[22:23]

.LBB0_1073:
	s_or_b64 exec, exec, s[12:13]
	s_waitcnt vmcnt(0)
	v_sub_f32_e32 v77, 1.0, v0
	ds_read_b32 v0, v80 offset:32768
	s_mul_i32 s13, s58, 0x3000
	s_mul_hi_i32 s12, s58, 0x3000
	s_add_u32 s24, s56, s13
	s_addc_u32 s25, s57, s12
	s_waitcnt lgkmcnt(0)
	v_cmp_gt_f32_e32 vcc, s75, v0
	v_mul_f32_e32 v1, 0x4f800000, v0
	s_lshl_b64 s[12:13], s[58:59], 9
	v_cndmask_b32_e32 v0, v0, v1, vcc
	v_sqrt_f32_e32 v1, v0
	v_lshl_add_u64 v[70:71], s[12:13], 0, v[106:107]
	v_add_u32_e32 v72, -1, v1
	v_fma_f32 v73, -v72, v1, v0
	v_cmp_ge_f32_e64 s[12:13], 0, v73
	v_add_u32_e32 v73, 1, v1
	s_nop 0
	v_cndmask_b32_e64 v72, v1, v72, s[12:13]
	v_fma_f32 v1, -v73, v1, v0
	v_cmp_lt_f32_e64 s[12:13], 0, v1
	s_nop 1
	v_cndmask_b32_e64 v1, v72, v73, s[12:13]
	v_mul_f32_e32 v72, 0x37800000, v1
	v_cndmask_b32_e32 v1, v1, v72, vcc
	v_cmp_class_f32_e32 vcc, v0, v250
	s_nop 1
	v_cndmask_b32_e32 v0, v1, v0, vcc
	v_max_f32_e32 v0, 0x2b8cbccc, v0
	v_div_scale_f32 v1, s[12:13], v0, v0, v104
	v_rcp_f32_e32 v72, v1
	s_mov_b32 s12, 0x4480000
	v_fma_f32 v73, -v1, v72, 1.0
	v_fmac_f32_e32 v72, v73, v72
	v_div_scale_f32 v73, vcc, v104, v0, v104
	v_mul_f32_e32 v105, v73, v72
	v_fma_f32 v108, -v1, v105, v73
	v_fmac_f32_e32 v105, v108, v72
	v_fma_f32 v1, -v1, v105, v73
	v_div_fmas_f32 v1, v1, v72, v105
	v_div_fixup_f32 v72, v1, v0, v104
	v_add_co_u32_e32 v0, vcc, s12, v74
	s_mov_b32 s12, 0x55a0000
	s_nop 0
	v_addc_co_u32_e32 v1, vcc, 0, v75, vcc
	global_store_dword v[0:1], v72, off
	v_add_co_u32_e32 v0, vcc, s12, v74
	v_mul_f32_e32 v72, v103, v72
	s_nop 0
	v_addc_co_u32_e32 v1, vcc, 0, v75, vcc
	global_store_dword v[0:1], v72, off
	v_lshl_add_u64 v[0:1], v[106:107], 1, s[24:25]
	s_movk_i32 s12, 0x1000
	v_add_co_u32_e32 v74, vcc, s12, v0
	s_nop 1
	v_addc_co_u32_e32 v75, vcc, 0, v1, vcc
	v_mov_b32_e32 v72, v137
	v_lshlrev_b32_e32 v72, 16, v72
	v_mov_b32_e32 v74, v214
	v_mul_f32_e32 v73, 0xbfb8aa3b, v72
	v_fma_f32 v103, v72, s33, -v73
	v_rndne_f32_e32 v104, v73
	v_fmac_f32_e32 v103, 0xb2a5705f, v72
	v_sub_f32_e32 v73, v73, v104
	v_add_f32_e32 v73, v73, v103
	v_exp_f32_e32 v73, v73
	v_cvt_i32_f32_e32 v103, v104
	v_cmp_nlt_f32_e32 vcc, s72, v72
	v_ldexp_f32 v73, v73, v103
	s_nop 0
	v_cndmask_b32_e32 v73, 0, v73, vcc
	v_cmp_ngt_f32_e32 vcc, s79, v72
	v_lshlrev_b32_e32 v74, 16, v74
	v_cndmask_b32_e32 v73, v220, v73, vcc
	v_add_f32_e32 v73, 1.0, v73
	v_div_scale_f32 v103, s[12:13], v73, v73, 1.0
	v_rcp_f32_e32 v104, v103
	v_mul_f32_e32 v75, 0x3fb8aa3b, v74
	v_fma_f32 v105, -v103, v104, 1.0
	v_fmac_f32_e32 v104, v105, v104
	v_div_scale_f32 v105, vcc, 1.0, v73, 1.0
	v_mul_f32_e32 v108, v105, v104
	v_fma_f32 v109, -v103, v108, v105
	v_fmac_f32_e32 v108, v109, v104
	v_fma_f32 v103, -v103, v108, v105
	v_div_fmas_f32 v103, v103, v104, v108
	v_div_fixup_f32 v73, v103, v73, 1.0
	v_mul_f32_e32 v103, v73, v72
	v_lshlrev_b64 v[72:73], 2, v[70:71]
	v_lshl_add_u64 v[104:105], s[14:15], 0, v[72:73]
	global_store_dword v[104:105], v103, off
	v_fma_f32 v103, v74, s65, -v75
	v_rndne_f32_e32 v104, v75
	v_fmac_f32_e32 v103, 0x32a5705f, v74
	v_sub_f32_e32 v75, v75, v104
	v_add_f32_e32 v75, v75, v103
	v_exp_f32_e32 v75, v75
	v_cvt_i32_f32_e32 v103, v104
	v_cmp_ngt_f32_e32 vcc, s47, v74
	v_lshl_add_u64 v[72:73], s[16:17], 0, v[72:73]
	v_ldexp_f32 v75, v75, v103
	v_cndmask_b32_e32 v75, 0, v75, vcc
	v_cmp_nlt_f32_e32 vcc, s37, v74
	s_nop 1
	v_cndmask_b32_e32 v74, v220, v75, vcc
	v_add_f32_e32 v74, 1.0, v74
	v_div_scale_f32 v75, s[12:13], v74, v74, 1.0
	v_rcp_f32_e32 v103, v75
	s_nop 0
	v_fma_f32 v104, -v75, v103, 1.0
	v_fmac_f32_e32 v103, v104, v103
	v_div_scale_f32 v104, vcc, 1.0, v74, 1.0
	v_mul_f32_e32 v105, v104, v103
	v_fma_f32 v108, -v75, v105, v104
	v_fmac_f32_e32 v105, v108, v103
	v_fma_f32 v75, -v75, v105, v104
	v_div_fmas_f32 v75, v75, v103, v105
	v_div_fixup_f32 v74, v75, v74, 1.0
	v_mul_f32_e32 v74, v77, v74
	v_min_f32_e32 v74, 0x3f7ff972, v74
	global_store_dword v[72:73], v74, off
	s_and_saveexec_b64 s[12:13], s[6:7]
	s_cbranch_execz .LBB0_1075
	v_mov_b64_e32 v[72:73], v[178:179]
	v_mov_b64_e32 v[74:75], v[180:181]
	s_lshl_b64 s[58:59], s[58:59], 8
	v_lshlrev_b32_e32 v103, 16, v72
	v_fma_f32 v103, v95, v103, v76
	v_and_b32_e32 v72, 0xffff0000, v72
	v_fmac_f32_e32 v103, v94, v72
	v_lshlrev_b32_e32 v72, 16, v73
	v_fmac_f32_e32 v103, v93, v72
	v_and_b32_e32 v72, 0xffff0000, v73
	v_fmac_f32_e32 v103, v92, v72
	v_lshlrev_b32_e32 v72, 16, v74
	v_fmac_f32_e32 v103, v91, v72
	v_and_b32_e32 v72, 0xffff0000, v74
	v_fmac_f32_e32 v103, v90, v72
	v_bfi_b32 v73, v237, 0, v75
	v_lshlrev_b32_e32 v72, 16, v75
	v_pk_mul_f32 v[72:73], v[64:65], v[72:73]
	s_nop 0
	v_add_f32_e32 v72, v103, v72
	v_add_f32_e32 v103, v72, v73
	v_mov_b64_e32 v[72:73], v[194:195]
	v_mov_b64_e32 v[74:75], v[196:197]
	v_bfi_b32 v105, v237, 0, v72
	v_lshlrev_b32_e32 v104, 16, v72
	v_pk_mul_f32 v[104:105], v[62:63], v[104:105]
	s_nop 0
	v_add_f32_e32 v72, v103, v104
	v_add_f32_e32 v103, v72, v105
	v_bfi_b32 v105, v237, 0, v73
	v_lshlrev_b32_e32 v104, 16, v73
	v_pk_mul_f32 v[72:73], v[60:61], v[104:105]
	s_nop 0
	v_add_f32_e32 v72, v103, v72
	v_add_f32_e32 v103, v72, v73
	v_bfi_b32 v73, v237, 0, v74
	v_lshlrev_b32_e32 v72, 16, v74
	v_pk_mul_f32 v[72:73], v[58:59], v[72:73]
	s_nop 0
	v_add_f32_e32 v72, v103, v72
	v_add_f32_e32 v74, v72, v73
	v_bfi_b32 v73, v237, 0, v75
	v_lshlrev_b32_e32 v72, 16, v75
	v_pk_mul_f32 v[72:73], v[56:57], v[72:73]
	s_nop 0
	v_add_f32_e32 v72, v74, v72
	v_add_f32_e32 v74, v72, v73
	v_add_co_u32_e32 v72, vcc, s74, v0
	s_nop 1
	v_addc_co_u32_e32 v73, vcc, 0, v1, vcc
	v_mov_b32_e32 v72, v233
	v_subrev_co_u32_e32 v70, vcc, s58, v70
	v_lshlrev_b32_e32 v72, 16, v72
	v_mul_f32_e32 v75, 0x3e000000, v72
	v_mov_b32_e32 v72, s59
	v_subb_co_u32_e32 v71, vcc, v71, v72, vcc
	v_lshlrev_b64 v[70:71], 2, v[70:71]
	v_lshl_add_u64 v[72:73], s[18:19], 0, v[70:71]
	global_store_dword v[72:73], v75, off
	v_mul_f32_e64 v73, |v74|, s33
	v_fma_f32 v75, |v74|, s33, -v73
	v_rndne_f32_e32 v103, v73
	v_fma_f32 v75, |v74|, s71, v75
	v_sub_f32_e32 v73, v73, v103
	v_add_f32_e32 v73, v73, v75
	v_exp_f32_e32 v73, v73
	v_cvt_i32_f32_e32 v75, v103
	v_cmp_ngt_f32_e64 vcc, |v74|, s72
	v_min_f32_e32 v72, 0, v74
	v_lshl_add_u64 v[70:71], s[20:21], 0, v[70:71]
	v_ldexp_f32 v73, v73, v75
	v_cndmask_b32_e32 v73, 0, v73, vcc
	v_cmp_nlt_f32_e64 vcc, |v74|, s79
	s_nop 1
	v_cndmask_b32_e32 v73, v220, v73, vcc
	v_add_f32_e32 v103, 1.0, v73
	v_add_f32_e32 v74, -1.0, v103
	v_sub_f32_e32 v75, v74, v103
	v_add_f32_e32 v75, 1.0, v75
	v_sub_f32_e32 v74, v73, v74
	v_add_f32_e32 v104, v74, v75
	v_frexp_mant_f32_e32 v74, v103
	v_cmp_gt_f32_e32 vcc, s76, v74
	v_cvt_f64_f32_e32 v[74:75], v103
	v_frexp_exp_i32_f64_e32 v74, v[74:75]
	v_subbrev_co_u32_e32 v74, vcc, 0, v74, vcc
	v_sub_u32_e32 v75, 0, v74
	v_ldexp_f32 v103, v103, v75
	v_ldexp_f32 v75, v104, v75
	v_add_f32_e32 v104, -1.0, v103
	v_add_f32_e32 v105, 1.0, v104
	v_sub_f32_e32 v105, v103, v105
	v_add_f32_e32 v105, v75, v105
	v_add_f32_e32 v108, v104, v105
	v_sub_f32_e32 v104, v104, v108
	v_add_f32_e32 v104, v105, v104
	v_add_f32_e32 v105, 1.0, v103
	v_add_f32_e32 v109, -1.0, v105
	v_sub_f32_e32 v103, v103, v109
	v_add_f32_e32 v75, v75, v103
	v_add_f32_e32 v103, v105, v75
	v_sub_f32_e32 v105, v105, v103
	v_add_f32_e32 v75, v75, v105
	v_rcp_f32_e32 v105, v103
	v_cvt_f32_i32_e32 v74, v74
	v_cmp_neq_f32_e32 vcc, s49, v73
	v_mul_f32_e32 v109, v108, v105
	v_mul_f32_e32 v110, v103, v109
	v_fma_f32 v111, v109, v103, -v110
	v_fmac_f32_e32 v111, v109, v75
	v_add_f32_e32 v112, v110, v111
	v_sub_f32_e32 v113, v108, v112
	v_sub_f32_e32 v108, v108, v113
	v_sub_f32_e32 v110, v112, v110
	v_sub_f32_e32 v108, v108, v112
	v_add_f32_e32 v104, v104, v108
	v_sub_f32_e32 v108, v110, v111
	v_add_f32_e32 v104, v108, v104
	v_add_f32_e32 v108, v113, v104
	v_mul_f32_e32 v110, v105, v108
	v_mul_f32_e32 v111, v103, v110
	v_fma_f32 v103, v110, v103, -v111
	v_fmac_f32_e32 v103, v110, v75
	v_sub_f32_e32 v75, v113, v108
	v_add_f32_e32 v75, v104, v75
	v_add_f32_e32 v104, v111, v103
	v_sub_f32_e32 v112, v108, v104
	v_sub_f32_e32 v108, v108, v112
	v_sub_f32_e32 v111, v104, v111
	v_sub_f32_e32 v104, v108, v104
	v_add_f32_e32 v75, v75, v104
	v_sub_f32_e32 v103, v111, v103
	v_add_f32_e32 v75, v103, v75
	v_add_f32_e32 v103, v109, v110
	v_add_f32_e32 v75, v112, v75
	v_sub_f32_e32 v104, v103, v109
	v_mul_f32_e32 v75, v105, v75
	v_sub_f32_e32 v104, v110, v104
	v_add_f32_e32 v75, v104, v75
	v_mul_f32_e32 v109, 0x3f317218, v74
	v_add_f32_e32 v104, v103, v75
	v_fma_f32 v110, v74, s77, -v109
	v_mul_f32_e32 v105, v104, v104
	v_fmac_f32_e32 v110, 0xb102e308, v74
	v_sub_f32_e32 v74, v104, v103
	v_fmamk_f32 v108, v105, 0x3e9b6dac, v230
	v_sub_f32_e32 v74, v75, v74
	v_add_f32_e32 v75, v109, v110
	v_fmaak_f32 v108, v105, v108, 0x3f2aaada
	v_sub_f32_e32 v103, v75, v109
	v_ldexp_f32 v109, v104, 1
	v_mul_f32_e32 v104, v104, v105
	v_mul_f32_e32 v104, v104, v108
	v_add_f32_e32 v105, v109, v104
	v_sub_f32_e32 v108, v105, v109
	v_ldexp_f32 v74, v74, 1
	v_sub_f32_e32 v104, v104, v108
	v_add_f32_e32 v74, v74, v104
	v_add_f32_e32 v104, v105, v74
	v_sub_f32_e32 v105, v104, v105
	v_sub_f32_e32 v74, v74, v105
	v_add_f32_e32 v105, v75, v104
	v_sub_f32_e32 v108, v105, v75
	v_sub_f32_e32 v109, v105, v108
	v_sub_f32_e32 v103, v110, v103
	v_sub_f32_e32 v75, v75, v109
	v_sub_f32_e32 v104, v104, v108
	v_add_f32_e32 v75, v104, v75
	v_add_f32_e32 v104, v103, v74
	v_sub_f32_e32 v108, v104, v103
	v_sub_f32_e32 v109, v104, v108
	v_sub_f32_e32 v103, v103, v109
	v_sub_f32_e32 v74, v74, v108
	v_add_f32_e32 v75, v104, v75
	v_add_f32_e32 v74, v74, v103
	v_add_f32_e32 v103, v105, v75
	v_sub_f32_e32 v104, v103, v105
	v_sub_f32_e32 v75, v75, v104
	v_add_f32_e32 v74, v74, v75
	v_add_f32_e32 v74, v103, v74
	v_cndmask_b32_e32 v74, v220, v74, vcc
	v_cmp_lt_f32_e64 vcc, |v73|, s78
	s_nop 1
	v_cndmask_b32_e32 v73, v74, v73, vcc
	v_sub_f32_e32 v72, v72, v73
	v_mul_f32_e32 v72, 0x3d800000, v72
	v_mul_f32_e32 v73, 0x3fb8aa3b, v72
	v_fma_f32 v74, v72, s65, -v73
	v_rndne_f32_e32 v75, v73
	v_fmac_f32_e32 v74, 0x32a5705f, v72
	v_sub_f32_e32 v73, v73, v75
	v_add_f32_e32 v73, v73, v74
	v_exp_f32_e32 v73, v73
	v_cvt_i32_f32_e32 v74, v75
	v_cmp_ngt_f32_e32 vcc, s47, v72
	v_ldexp_f32 v73, v73, v74
	s_nop 0
	v_cndmask_b32_e32 v73, 0, v73, vcc
	v_cmp_nlt_f32_e32 vcc, s37, v72
	s_nop 1
	v_cndmask_b32_e32 v72, v220, v73, vcc
	global_store_dword v[70:71], v72, off
.LBB0_1075:
	s_or_b64 exec, exec, s[12:13]
	ds_read_b32 v72, v80 offset:32800
	s_lshl_b64 s[12:13], s[30:31], 9
	v_lshl_add_u64 v[70:71], s[12:13], 0, v[106:107]
	s_waitcnt lgkmcnt(0)
	v_cmp_gt_f32_e32 vcc, s75, v72
	v_mul_f32_e32 v73, 0x4f800000, v72
	s_nop 0
	v_cndmask_b32_e32 v72, v72, v73, vcc
	v_sqrt_f32_e32 v73, v72
	s_nop 0
	v_add_u32_e32 v74, -1, v73
	v_fma_f32 v75, -v74, v73, v72
	v_cmp_ge_f32_e64 s[12:13], 0, v75
	v_add_u32_e32 v75, 1, v73
	s_nop 0
	v_cndmask_b32_e64 v74, v73, v74, s[12:13]
	v_fma_f32 v73, -v75, v73, v72
	v_cmp_lt_f32_e64 s[12:13], 0, v73
	s_nop 1
	v_cndmask_b32_e64 v73, v74, v75, s[12:13]
	v_mul_f32_e32 v74, 0x37800000, v73
	v_cndmask_b32_e32 v73, v73, v74, vcc
	v_cmp_class_f32_e32 vcc, v72, v250
	s_nop 1
	v_cndmask_b32_e32 v72, v73, v72, vcc
	v_max_f32_e32 v72, 0x2b8cbccc, v72
	v_div_scale_f32 v73, s[12:13], v72, v72, v102
	v_rcp_f32_e32 v74, v73
	s_mov_b32 s12, 0x4480000
	v_fma_f32 v75, -v73, v74, 1.0
	v_fmac_f32_e32 v74, v75, v74
	v_div_scale_f32 v75, vcc, v102, v72, v102
	v_mul_f32_e32 v103, v75, v74
	v_fma_f32 v104, -v73, v103, v75
	v_fmac_f32_e32 v103, v104, v74
	v_fma_f32 v73, -v73, v103, v75
	v_div_fmas_f32 v73, v73, v74, v103
	v_div_fixup_f32 v74, v73, v72, v102
	v_add_co_u32_e32 v72, vcc, s12, v68
	s_mov_b32 s12, 0x55a0000
	s_nop 0
	v_addc_co_u32_e32 v73, vcc, 0, v69, vcc
	v_add_co_u32_e32 v68, vcc, s12, v68
	global_store_dword v[72:73], v74, off
	v_mul_f32_e32 v72, v101, v74
	v_addc_co_u32_e32 v69, vcc, 0, v69, vcc
	global_store_dword v[68:69], v72, off
	v_add_co_u32_e32 v72, vcc, s52, v0
	s_nop 1
	v_addc_co_u32_e32 v73, vcc, 0, v1, vcc
	v_mov_b32_e32 v68, v234
	v_lshlrev_b32_e32 v68, 16, v68
	v_mov_b32_e32 v72, v235
	v_mul_f32_e32 v69, 0xbfb8aa3b, v68
	v_fma_f32 v74, v68, s33, -v69
	v_rndne_f32_e32 v75, v69
	v_fmac_f32_e32 v74, 0xb2a5705f, v68
	v_sub_f32_e32 v69, v69, v75
	v_add_f32_e32 v69, v69, v74
	v_exp_f32_e32 v69, v69
	v_cvt_i32_f32_e32 v74, v75
	v_cmp_nlt_f32_e32 vcc, s72, v68
	v_ldexp_f32 v69, v69, v74
	s_nop 0
	v_cndmask_b32_e32 v69, 0, v69, vcc
	v_cmp_ngt_f32_e32 vcc, s79, v68
	v_lshlrev_b32_e32 v72, 16, v72
	v_cndmask_b32_e32 v69, v220, v69, vcc
	v_add_f32_e32 v69, 1.0, v69
	v_div_scale_f32 v74, s[12:13], v69, v69, 1.0
	v_rcp_f32_e32 v75, v74
	v_mul_f32_e32 v73, 0x3fb8aa3b, v72
	v_fma_f32 v101, -v74, v75, 1.0
	v_fmac_f32_e32 v75, v101, v75
	v_div_scale_f32 v101, vcc, 1.0, v69, 1.0
	v_mul_f32_e32 v102, v101, v75
	v_fma_f32 v103, -v74, v102, v101
	v_fmac_f32_e32 v102, v103, v75
	v_fma_f32 v74, -v74, v102, v101
	v_div_fmas_f32 v74, v74, v75, v102
	v_div_fixup_f32 v69, v74, v69, 1.0
	v_mul_f32_e32 v101, v69, v68
	v_lshlrev_b64 v[68:69], 2, v[70:71]
	v_lshl_add_u64 v[74:75], s[14:15], 0, v[68:69]
	global_store_dword v[74:75], v101, off
	v_fma_f32 v74, v72, s65, -v73
	v_rndne_f32_e32 v75, v73
	v_fmac_f32_e32 v74, 0x32a5705f, v72
	v_sub_f32_e32 v73, v73, v75
	v_add_f32_e32 v73, v73, v74
	v_exp_f32_e32 v73, v73
	v_cvt_i32_f32_e32 v74, v75
	v_cmp_ngt_f32_e32 vcc, s47, v72
	v_lshl_add_u64 v[68:69], s[16:17], 0, v[68:69]
	v_ldexp_f32 v73, v73, v74
	v_cndmask_b32_e32 v73, 0, v73, vcc
	v_cmp_nlt_f32_e32 vcc, s37, v72
	s_nop 1
	v_cndmask_b32_e32 v72, v220, v73, vcc
	v_add_f32_e32 v72, 1.0, v72
	v_div_scale_f32 v73, s[12:13], v72, v72, 1.0
	v_rcp_f32_e32 v74, v73
	s_nop 0
	v_fma_f32 v75, -v73, v74, 1.0
	v_fmac_f32_e32 v74, v75, v74
	v_div_scale_f32 v75, vcc, 1.0, v72, 1.0
	v_mul_f32_e32 v101, v75, v74
	v_fma_f32 v102, -v73, v101, v75
	v_fmac_f32_e32 v101, v102, v74
	v_fma_f32 v73, -v73, v101, v75
	v_div_fmas_f32 v73, v73, v74, v101
	v_div_fixup_f32 v72, v73, v72, 1.0
	v_mul_f32_e32 v72, v77, v72
	v_min_f32_e32 v72, 0x3f7ff972, v72
	global_store_dword v[68:69], v72, off
	s_and_saveexec_b64 s[12:13], s[6:7]
	s_cbranch_execz .LBB0_1077
	v_mov_b32_e32 v102, 0x5000
	v_mov_b64_e32 v[72:73], v[198:199]
	v_mov_b64_e32 v[74:75], v[200:201]
	v_lshl_add_u64 v[68:69], v[0:1], 0, s[80:81]
	v_add_co_u32_e32 v68, vcc, s74, v68
	s_lshl_b64 s[30:31], s[30:31], 8
	s_nop 0
	v_addc_co_u32_e32 v69, vcc, 0, v69, vcc
	v_mov_b32_e32 v68, v236
	v_mov_b32_e32 v69, s31
	v_lshlrev_b32_e32 v101, 16, v72
	v_fma_f32 v101, v95, v101, v76
	v_and_b32_e32 v72, 0xffff0000, v72
	v_fmac_f32_e32 v101, v94, v72
	v_lshlrev_b32_e32 v72, 16, v73
	v_fmac_f32_e32 v101, v93, v72
	v_and_b32_e32 v72, 0xffff0000, v73
	v_fmac_f32_e32 v101, v92, v72
	v_lshlrev_b32_e32 v72, 16, v74
	v_fmac_f32_e32 v101, v91, v72
	v_and_b32_e32 v72, 0xffff0000, v74
	v_fmac_f32_e32 v101, v90, v72
	v_bfi_b32 v73, v237, 0, v75
	v_lshlrev_b32_e32 v72, 16, v75
	v_pk_mul_f32 v[72:73], v[64:65], v[72:73]
	v_lshlrev_b32_e32 v68, 16, v68
	v_add_f32_e32 v72, v101, v72
	v_add_f32_e32 v101, v72, v73
	v_mov_b64_e32 v[72:73], v[202:203]
	v_mov_b64_e32 v[74:75], v[204:205]
	v_bfi_b32 v103, v237, 0, v72
	v_lshlrev_b32_e32 v102, 16, v72
	v_pk_mul_f32 v[102:103], v[62:63], v[102:103]
	s_nop 0
	v_add_f32_e32 v72, v101, v102
	v_add_f32_e32 v101, v72, v103
	v_bfi_b32 v103, v237, 0, v73
	v_lshlrev_b32_e32 v102, 16, v73
	v_pk_mul_f32 v[72:73], v[60:61], v[102:103]
	s_nop 0
	v_add_f32_e32 v72, v101, v72
	v_add_f32_e32 v101, v72, v73
	v_bfi_b32 v73, v237, 0, v74
	v_lshlrev_b32_e32 v72, 16, v74
	v_pk_mul_f32 v[72:73], v[58:59], v[72:73]
	s_nop 0
	v_add_f32_e32 v72, v101, v72
	v_add_f32_e32 v74, v72, v73
	v_bfi_b32 v73, v237, 0, v75
	v_lshlrev_b32_e32 v72, 16, v75
	v_pk_mul_f32 v[72:73], v[56:57], v[72:73]
	s_nop 0
	v_add_f32_e32 v72, v74, v72
	v_add_f32_e32 v72, v72, v73
	v_mul_f32_e32 v73, 0x3e000000, v68
	v_subrev_co_u32_e32 v68, vcc, s30, v70
	s_nop 1
	v_subb_co_u32_e32 v69, vcc, v71, v69, vcc
	v_lshlrev_b64 v[68:69], 2, v[68:69]
	v_lshl_add_u64 v[70:71], s[18:19], 0, v[68:69]
	global_store_dword v[70:71], v73, off
	v_mul_f32_e64 v71, |v72|, s33
	v_fma_f32 v73, |v72|, s33, -v71
	v_rndne_f32_e32 v74, v71
	v_fma_f32 v73, |v72|, s71, v73
	v_sub_f32_e32 v71, v71, v74
	v_add_f32_e32 v71, v71, v73
	v_exp_f32_e32 v71, v71
	v_cvt_i32_f32_e32 v73, v74
	v_cmp_ngt_f32_e64 vcc, |v72|, s72
	v_min_f32_e32 v70, 0, v72
	v_lshl_add_u64 v[68:69], s[20:21], 0, v[68:69]
	v_ldexp_f32 v71, v71, v73
	v_cndmask_b32_e32 v71, 0, v71, vcc
	v_cmp_nlt_f32_e64 vcc, |v72|, s79
	s_nop 1
	v_cndmask_b32_e32 v71, v220, v71, vcc
	v_add_f32_e32 v74, 1.0, v71
	v_add_f32_e32 v72, -1.0, v74
	v_sub_f32_e32 v73, v72, v74
	v_add_f32_e32 v73, 1.0, v73
	v_sub_f32_e32 v72, v71, v72
	v_add_f32_e32 v75, v72, v73
	v_frexp_mant_f32_e32 v72, v74
	v_cmp_gt_f32_e32 vcc, s76, v72
	v_cvt_f64_f32_e32 v[72:73], v74
	v_frexp_exp_i32_f64_e32 v72, v[72:73]
	v_subbrev_co_u32_e32 v72, vcc, 0, v72, vcc
	v_sub_u32_e32 v73, 0, v72
	v_ldexp_f32 v74, v74, v73
	v_ldexp_f32 v73, v75, v73
	v_add_f32_e32 v75, -1.0, v74
	v_add_f32_e32 v101, 1.0, v75
	v_sub_f32_e32 v101, v74, v101
	v_add_f32_e32 v101, v73, v101
	v_add_f32_e32 v102, v75, v101
	v_sub_f32_e32 v75, v75, v102
	v_add_f32_e32 v75, v101, v75
	v_add_f32_e32 v101, 1.0, v74
	v_add_f32_e32 v103, -1.0, v101
	v_sub_f32_e32 v74, v74, v103
	v_add_f32_e32 v73, v73, v74
	v_add_f32_e32 v74, v101, v73
	v_sub_f32_e32 v101, v101, v74
	v_add_f32_e32 v73, v73, v101
	v_rcp_f32_e32 v101, v74
	v_cvt_f32_i32_e32 v72, v72
	v_cmp_neq_f32_e32 vcc, s49, v71
	v_mul_f32_e32 v103, v102, v101
	v_mul_f32_e32 v104, v74, v103
	v_fma_f32 v105, v103, v74, -v104
	v_fmac_f32_e32 v105, v103, v73
	v_add_f32_e32 v108, v104, v105
	v_sub_f32_e32 v109, v102, v108
	v_sub_f32_e32 v102, v102, v109
	v_sub_f32_e32 v104, v108, v104
	v_sub_f32_e32 v102, v102, v108
	v_add_f32_e32 v75, v75, v102
	v_sub_f32_e32 v102, v104, v105
	v_add_f32_e32 v75, v102, v75
	v_add_f32_e32 v102, v109, v75
	v_mul_f32_e32 v104, v101, v102
	v_mul_f32_e32 v105, v74, v104
	v_fma_f32 v74, v104, v74, -v105
	v_fmac_f32_e32 v74, v104, v73
	v_sub_f32_e32 v73, v109, v102
	v_add_f32_e32 v73, v75, v73
	v_add_f32_e32 v75, v105, v74
	v_sub_f32_e32 v108, v102, v75
	v_sub_f32_e32 v102, v102, v108
	v_sub_f32_e32 v105, v75, v105
	v_sub_f32_e32 v75, v102, v75
	v_add_f32_e32 v73, v73, v75
	v_sub_f32_e32 v74, v105, v74
	v_add_f32_e32 v73, v74, v73
	v_add_f32_e32 v74, v103, v104
	v_add_f32_e32 v73, v108, v73
	v_sub_f32_e32 v75, v74, v103
	v_mul_f32_e32 v73, v101, v73
	v_sub_f32_e32 v75, v104, v75
	v_add_f32_e32 v73, v75, v73
	v_mul_f32_e32 v103, 0x3f317218, v72
	v_add_f32_e32 v75, v74, v73
	v_fma_f32 v104, v72, s77, -v103
	v_mul_f32_e32 v101, v75, v75
	v_fmac_f32_e32 v104, 0xb102e308, v72
	v_sub_f32_e32 v72, v75, v74
	v_fmamk_f32 v102, v101, 0x3e9b6dac, v230
	v_sub_f32_e32 v72, v73, v72
	v_add_f32_e32 v73, v103, v104
	v_fmaak_f32 v102, v101, v102, 0x3f2aaada
	v_sub_f32_e32 v74, v73, v103
	v_ldexp_f32 v103, v75, 1
	v_mul_f32_e32 v75, v75, v101
	v_mul_f32_e32 v75, v75, v102
	v_add_f32_e32 v101, v103, v75
	v_sub_f32_e32 v102, v101, v103
	v_ldexp_f32 v72, v72, 1
	v_sub_f32_e32 v75, v75, v102
	v_add_f32_e32 v72, v72, v75
	v_add_f32_e32 v75, v101, v72
	v_sub_f32_e32 v101, v75, v101
	v_sub_f32_e32 v72, v72, v101
	v_add_f32_e32 v101, v73, v75
	v_sub_f32_e32 v102, v101, v73
	v_sub_f32_e32 v103, v101, v102
	v_sub_f32_e32 v74, v104, v74
	v_sub_f32_e32 v73, v73, v103
	v_sub_f32_e32 v75, v75, v102
	v_add_f32_e32 v73, v75, v73
	v_add_f32_e32 v75, v74, v72
	v_sub_f32_e32 v102, v75, v74
	v_sub_f32_e32 v103, v75, v102
	v_sub_f32_e32 v74, v74, v103
	v_sub_f32_e32 v72, v72, v102
	v_add_f32_e32 v73, v75, v73
	v_add_f32_e32 v72, v72, v74
	v_add_f32_e32 v74, v101, v73
	v_sub_f32_e32 v75, v74, v101
	v_sub_f32_e32 v73, v73, v75
	v_add_f32_e32 v72, v72, v73
	v_add_f32_e32 v72, v74, v72
	v_cndmask_b32_e32 v72, v220, v72, vcc
	v_cmp_lt_f32_e64 vcc, |v71|, s78
	s_nop 1
	v_cndmask_b32_e32 v71, v72, v71, vcc
	v_sub_f32_e32 v70, v70, v71
	v_mul_f32_e32 v70, 0x3d800000, v70
	v_mul_f32_e32 v71, 0x3fb8aa3b, v70
	v_fma_f32 v72, v70, s65, -v71
	v_rndne_f32_e32 v73, v71
	v_fmac_f32_e32 v72, 0x32a5705f, v70
	v_sub_f32_e32 v71, v71, v73
	v_add_f32_e32 v71, v71, v72
	v_exp_f32_e32 v71, v71
	v_cvt_i32_f32_e32 v72, v73
	v_cmp_ngt_f32_e32 vcc, s47, v70
	v_ldexp_f32 v71, v71, v72
	s_nop 0
	v_cndmask_b32_e32 v71, 0, v71, vcc
	v_cmp_nlt_f32_e32 vcc, s37, v70
	s_nop 1
	v_cndmask_b32_e32 v70, v220, v71, vcc
	global_store_dword v[68:69], v70, off
.LBB0_1077:
	s_or_b64 exec, exec, s[12:13]
	ds_read_b32 v70, v80 offset:32832
	s_lshl_b64 s[12:13], s[26:27], 9
	v_lshl_add_u64 v[68:69], s[12:13], 0, v[106:107]
	s_waitcnt lgkmcnt(0)
	v_cmp_gt_f32_e32 vcc, s75, v70
	v_mul_f32_e32 v71, 0x4f800000, v70
	s_nop 0
	v_cndmask_b32_e32 v70, v70, v71, vcc
	v_sqrt_f32_e32 v71, v70
	s_nop 0
	v_add_u32_e32 v72, -1, v71
	v_fma_f32 v73, -v72, v71, v70
	v_cmp_ge_f32_e64 s[12:13], 0, v73
	v_add_u32_e32 v73, 1, v71
	s_nop 0
	v_cndmask_b32_e64 v72, v71, v72, s[12:13]
	v_fma_f32 v71, -v73, v71, v70
	v_cmp_lt_f32_e64 s[12:13], 0, v71
	s_nop 1
	v_cndmask_b32_e64 v71, v72, v73, s[12:13]
	v_mul_f32_e32 v72, 0x37800000, v71
	v_cndmask_b32_e32 v71, v71, v72, vcc
	v_cmp_class_f32_e32 vcc, v70, v250
	s_nop 1
	v_cndmask_b32_e32 v70, v71, v70, vcc
	v_max_f32_e32 v70, 0x2b8cbccc, v70
	v_div_scale_f32 v71, s[12:13], v70, v70, v100
	v_rcp_f32_e32 v72, v71
	s_mov_b32 s12, 0x4480000
	v_fma_f32 v73, -v71, v72, 1.0
	v_fmac_f32_e32 v72, v73, v72
	v_div_scale_f32 v73, vcc, v100, v70, v100
	v_mul_f32_e32 v74, v73, v72
	v_fma_f32 v75, -v71, v74, v73
	v_fmac_f32_e32 v74, v75, v72
	v_fma_f32 v71, -v71, v74, v73
	v_div_fmas_f32 v71, v71, v72, v74
	v_div_fixup_f32 v72, v71, v70, v100
	v_add_co_u32_e32 v70, vcc, s12, v66
	s_mov_b32 s12, 0x55a0000
	s_nop 0
	v_addc_co_u32_e32 v71, vcc, 0, v67, vcc
	v_add_co_u32_e32 v66, vcc, s12, v66
	global_store_dword v[70:71], v72, off
	v_mul_f32_e32 v70, v99, v72
	v_addc_co_u32_e32 v67, vcc, 0, v67, vcc
	global_store_dword v[66:67], v70, off
	v_add_co_u32_e32 v70, vcc, s69, v0
	s_nop 1
	v_addc_co_u32_e32 v71, vcc, 0, v1, vcc
	v_mov_b32_e32 v66, v244
	v_lshlrev_b32_e32 v66, 16, v66
	v_mov_b32_e32 v70, v245
	v_mul_f32_e32 v67, 0xbfb8aa3b, v66
	v_fma_f32 v72, v66, s33, -v67
	v_rndne_f32_e32 v73, v67
	v_fmac_f32_e32 v72, 0xb2a5705f, v66
	v_sub_f32_e32 v67, v67, v73
	v_add_f32_e32 v67, v67, v72
	v_exp_f32_e32 v67, v67
	v_cvt_i32_f32_e32 v72, v73
	v_cmp_nlt_f32_e32 vcc, s72, v66
	v_ldexp_f32 v67, v67, v72
	s_nop 0
	v_cndmask_b32_e32 v67, 0, v67, vcc
	v_cmp_ngt_f32_e32 vcc, s79, v66
	v_lshlrev_b32_e32 v70, 16, v70
	v_cndmask_b32_e32 v67, v220, v67, vcc
	v_add_f32_e32 v67, 1.0, v67
	v_div_scale_f32 v72, s[12:13], v67, v67, 1.0
	v_rcp_f32_e32 v73, v72
	v_mul_f32_e32 v71, 0x3fb8aa3b, v70
	v_fma_f32 v74, -v72, v73, 1.0
	v_fmac_f32_e32 v73, v74, v73
	v_div_scale_f32 v74, vcc, 1.0, v67, 1.0
	v_mul_f32_e32 v75, v74, v73
	v_fma_f32 v99, -v72, v75, v74
	v_fmac_f32_e32 v75, v99, v73
	v_fma_f32 v72, -v72, v75, v74
	v_div_fmas_f32 v72, v72, v73, v75
	v_div_fixup_f32 v67, v72, v67, 1.0
	v_mul_f32_e32 v74, v67, v66
	v_lshlrev_b64 v[66:67], 2, v[68:69]
	v_lshl_add_u64 v[72:73], s[14:15], 0, v[66:67]
	global_store_dword v[72:73], v74, off
	v_fma_f32 v72, v70, s65, -v71
	v_rndne_f32_e32 v73, v71
	v_fmac_f32_e32 v72, 0x32a5705f, v70
	v_sub_f32_e32 v71, v71, v73
	v_add_f32_e32 v71, v71, v72
	v_exp_f32_e32 v71, v71
	v_cvt_i32_f32_e32 v72, v73
	v_cmp_ngt_f32_e32 vcc, s47, v70
	v_lshl_add_u64 v[66:67], s[16:17], 0, v[66:67]
	v_ldexp_f32 v71, v71, v72
	v_cndmask_b32_e32 v71, 0, v71, vcc
	v_cmp_nlt_f32_e32 vcc, s37, v70
	s_nop 1
	v_cndmask_b32_e32 v70, v220, v71, vcc
	v_add_f32_e32 v70, 1.0, v70
	v_div_scale_f32 v71, s[12:13], v70, v70, 1.0
	v_rcp_f32_e32 v72, v71
	s_nop 0
	v_fma_f32 v73, -v71, v72, 1.0
	v_fmac_f32_e32 v72, v73, v72
	v_div_scale_f32 v73, vcc, 1.0, v70, 1.0
	v_mul_f32_e32 v74, v73, v72
	v_fma_f32 v75, -v71, v74, v73
	v_fmac_f32_e32 v74, v75, v72
	v_fma_f32 v71, -v71, v74, v73
	v_div_fmas_f32 v71, v71, v72, v74
	v_div_fixup_f32 v70, v71, v70, 1.0
	v_mul_f32_e32 v70, v77, v70
	v_min_f32_e32 v70, 0x3f7ff972, v70
	global_store_dword v[66:67], v70, off
	s_and_saveexec_b64 s[12:13], s[6:7]
	s_cbranch_execz .LBB0_1079
	v_mov_b32_e32 v75, 0x8000
	v_mov_b64_e32 v[70:71], v[206:207]
	v_mov_b64_e32 v[72:73], v[208:209]
	v_lshl_add_u64 v[66:67], v[0:1], 0, s[82:83]
	v_add_co_u32_e32 v66, vcc, s74, v66
	s_lshl_b64 s[26:27], s[26:27], 8
	s_nop 0
	v_addc_co_u32_e32 v67, vcc, 0, v67, vcc
	v_mov_b32_e32 v66, v238
	v_mov_b32_e32 v67, s27
	v_lshlrev_b32_e32 v74, 16, v70
	v_fma_f32 v74, v95, v74, v76
	v_and_b32_e32 v70, 0xffff0000, v70
	v_fmac_f32_e32 v74, v94, v70
	v_lshlrev_b32_e32 v70, 16, v71
	v_fmac_f32_e32 v74, v93, v70
	v_and_b32_e32 v70, 0xffff0000, v71
	v_fmac_f32_e32 v74, v92, v70
	v_lshlrev_b32_e32 v70, 16, v72
	v_fmac_f32_e32 v74, v91, v70
	v_and_b32_e32 v70, 0xffff0000, v72
	v_fmac_f32_e32 v74, v90, v70
	v_bfi_b32 v71, v237, 0, v73
	v_lshlrev_b32_e32 v70, 16, v73
	v_pk_mul_f32 v[70:71], v[64:65], v[70:71]
	v_lshlrev_b32_e32 v66, 16, v66
	v_add_f32_e32 v70, v74, v70
	v_add_f32_e32 v99, v70, v71
	v_mov_b64_e32 v[70:71], v[210:211]
	v_mov_b64_e32 v[72:73], v[212:213]
	v_bfi_b32 v75, v237, 0, v70
	v_lshlrev_b32_e32 v74, 16, v70
	v_pk_mul_f32 v[74:75], v[62:63], v[74:75]
	s_nop 0
	v_add_f32_e32 v70, v99, v74
	v_add_f32_e32 v99, v70, v75
	v_bfi_b32 v75, v237, 0, v71
	v_lshlrev_b32_e32 v74, 16, v71
	v_pk_mul_f32 v[70:71], v[60:61], v[74:75]
	s_nop 0
	v_add_f32_e32 v70, v99, v70
	v_add_f32_e32 v74, v70, v71
	v_bfi_b32 v71, v237, 0, v72
	v_lshlrev_b32_e32 v70, 16, v72
	v_pk_mul_f32 v[70:71], v[58:59], v[70:71]
	s_nop 0
	v_add_f32_e32 v70, v74, v70
	v_add_f32_e32 v72, v70, v71
	v_bfi_b32 v71, v237, 0, v73
	v_lshlrev_b32_e32 v70, 16, v73
	v_pk_mul_f32 v[70:71], v[56:57], v[70:71]
	s_nop 0
	v_add_f32_e32 v70, v72, v70
	v_add_f32_e32 v70, v70, v71
	v_mul_f32_e32 v71, 0x3e000000, v66
	v_subrev_co_u32_e32 v66, vcc, s26, v68
	s_nop 1
	v_subb_co_u32_e32 v67, vcc, v69, v67, vcc
	v_lshlrev_b64 v[66:67], 2, v[66:67]
	v_lshl_add_u64 v[68:69], s[18:19], 0, v[66:67]
	global_store_dword v[68:69], v71, off
	v_mul_f32_e64 v69, |v70|, s33
	v_fma_f32 v71, |v70|, s33, -v69
	v_rndne_f32_e32 v72, v69
	v_fma_f32 v71, |v70|, s71, v71
	v_sub_f32_e32 v69, v69, v72
	v_add_f32_e32 v69, v69, v71
	v_exp_f32_e32 v69, v69
	v_cvt_i32_f32_e32 v71, v72
	v_cmp_ngt_f32_e64 vcc, |v70|, s72
	v_min_f32_e32 v68, 0, v70
	v_lshl_add_u64 v[66:67], s[20:21], 0, v[66:67]
	v_ldexp_f32 v69, v69, v71
	v_cndmask_b32_e32 v69, 0, v69, vcc
	v_cmp_nlt_f32_e64 vcc, |v70|, s79
	s_nop 1
	v_cndmask_b32_e32 v69, v220, v69, vcc
	v_add_f32_e32 v72, 1.0, v69
	v_add_f32_e32 v70, -1.0, v72
	v_sub_f32_e32 v71, v70, v72
	v_add_f32_e32 v71, 1.0, v71
	v_sub_f32_e32 v70, v69, v70
	v_add_f32_e32 v73, v70, v71
	v_frexp_mant_f32_e32 v70, v72
	v_cmp_gt_f32_e32 vcc, s76, v70
	v_cvt_f64_f32_e32 v[70:71], v72
	v_frexp_exp_i32_f64_e32 v70, v[70:71]
	v_subbrev_co_u32_e32 v70, vcc, 0, v70, vcc
	v_sub_u32_e32 v71, 0, v70
	v_ldexp_f32 v72, v72, v71
	v_ldexp_f32 v71, v73, v71
	v_add_f32_e32 v73, -1.0, v72
	v_add_f32_e32 v74, 1.0, v73
	v_sub_f32_e32 v74, v72, v74
	v_add_f32_e32 v74, v71, v74
	v_add_f32_e32 v75, v73, v74
	v_sub_f32_e32 v73, v73, v75
	v_add_f32_e32 v73, v74, v73
	v_add_f32_e32 v74, 1.0, v72
	v_add_f32_e32 v99, -1.0, v74
	v_sub_f32_e32 v72, v72, v99
	v_add_f32_e32 v71, v71, v72
	v_add_f32_e32 v72, v74, v71
	v_sub_f32_e32 v74, v74, v72
	v_add_f32_e32 v71, v71, v74
	v_rcp_f32_e32 v74, v72
	v_cvt_f32_i32_e32 v70, v70
	v_cmp_neq_f32_e32 vcc, s49, v69
	v_mul_f32_e32 v99, v75, v74
	v_mul_f32_e32 v100, v72, v99
	v_fma_f32 v101, v99, v72, -v100
	v_fmac_f32_e32 v101, v99, v71
	v_add_f32_e32 v102, v100, v101
	v_sub_f32_e32 v103, v75, v102
	v_sub_f32_e32 v75, v75, v103
	v_sub_f32_e32 v100, v102, v100
	v_sub_f32_e32 v75, v75, v102
	v_add_f32_e32 v73, v73, v75
	v_sub_f32_e32 v75, v100, v101
	v_add_f32_e32 v73, v75, v73
	v_add_f32_e32 v75, v103, v73
	v_mul_f32_e32 v100, v74, v75
	v_mul_f32_e32 v101, v72, v100
	v_fma_f32 v72, v100, v72, -v101
	v_fmac_f32_e32 v72, v100, v71
	v_sub_f32_e32 v71, v103, v75
	v_add_f32_e32 v71, v73, v71
	v_add_f32_e32 v73, v101, v72
	v_sub_f32_e32 v102, v75, v73
	v_sub_f32_e32 v75, v75, v102
	v_sub_f32_e32 v101, v73, v101
	v_sub_f32_e32 v73, v75, v73
	v_add_f32_e32 v71, v71, v73
	v_sub_f32_e32 v72, v101, v72
	v_add_f32_e32 v71, v72, v71
	v_add_f32_e32 v72, v99, v100
	v_add_f32_e32 v71, v102, v71
	v_sub_f32_e32 v73, v72, v99
	v_mul_f32_e32 v71, v74, v71
	v_sub_f32_e32 v73, v100, v73
	v_add_f32_e32 v71, v73, v71
	v_mul_f32_e32 v99, 0x3f317218, v70
	v_add_f32_e32 v73, v72, v71
	v_fma_f32 v100, v70, s77, -v99
	v_mul_f32_e32 v74, v73, v73
	v_fmac_f32_e32 v100, 0xb102e308, v70
	v_sub_f32_e32 v70, v73, v72
	v_fmamk_f32 v75, v74, 0x3e9b6dac, v230
	v_sub_f32_e32 v70, v71, v70
	v_add_f32_e32 v71, v99, v100
	v_fmaak_f32 v75, v74, v75, 0x3f2aaada
	v_sub_f32_e32 v72, v71, v99
	v_ldexp_f32 v99, v73, 1
	v_mul_f32_e32 v73, v73, v74
	v_mul_f32_e32 v73, v73, v75
	v_add_f32_e32 v74, v99, v73
	v_sub_f32_e32 v75, v74, v99
	v_ldexp_f32 v70, v70, 1
	v_sub_f32_e32 v73, v73, v75
	v_add_f32_e32 v70, v70, v73
	v_add_f32_e32 v73, v74, v70
	v_sub_f32_e32 v74, v73, v74
	v_sub_f32_e32 v70, v70, v74
	v_add_f32_e32 v74, v71, v73
	v_sub_f32_e32 v75, v74, v71
	v_sub_f32_e32 v99, v74, v75
	v_sub_f32_e32 v72, v100, v72
	v_sub_f32_e32 v71, v71, v99
	v_sub_f32_e32 v73, v73, v75
	v_add_f32_e32 v71, v73, v71
	v_add_f32_e32 v73, v72, v70
	v_sub_f32_e32 v75, v73, v72
	v_sub_f32_e32 v99, v73, v75
	v_sub_f32_e32 v72, v72, v99
	v_sub_f32_e32 v70, v70, v75
	v_add_f32_e32 v71, v73, v71
	v_add_f32_e32 v70, v70, v72
	v_add_f32_e32 v72, v74, v71
	v_sub_f32_e32 v73, v72, v74
	v_sub_f32_e32 v71, v71, v73
	v_add_f32_e32 v70, v70, v71
	v_add_f32_e32 v70, v72, v70
	v_cndmask_b32_e32 v70, v220, v70, vcc
	v_cmp_lt_f32_e64 vcc, |v69|, s78
	s_nop 1
	v_cndmask_b32_e32 v69, v70, v69, vcc
	v_sub_f32_e32 v68, v68, v69
	v_mul_f32_e32 v68, 0x3d800000, v68
	v_mul_f32_e32 v69, 0x3fb8aa3b, v68
	v_fma_f32 v70, v68, s65, -v69
	v_rndne_f32_e32 v71, v69
	v_fmac_f32_e32 v70, 0x32a5705f, v68
	v_sub_f32_e32 v69, v69, v71
	v_add_f32_e32 v69, v69, v70
	v_exp_f32_e32 v69, v69
	v_cvt_i32_f32_e32 v70, v71
	v_cmp_ngt_f32_e32 vcc, s47, v68
	v_ldexp_f32 v69, v69, v70
	s_nop 0
	v_cndmask_b32_e32 v69, 0, v69, vcc
	v_cmp_nlt_f32_e32 vcc, s37, v68
	s_nop 1
	v_cndmask_b32_e32 v68, v220, v69, vcc
	global_store_dword v[66:67], v68, off
.LBB0_1079:
	s_or_b64 exec, exec, s[12:13]
	ds_read_b32 v68, v80 offset:32864
	s_lshl_b64 s[12:13], s[22:23], 9
	v_lshl_add_u64 v[66:67], s[12:13], 0, v[106:107]
	s_waitcnt lgkmcnt(0)
	v_cmp_gt_f32_e32 vcc, s75, v68
	v_mul_f32_e32 v69, 0x4f800000, v68
	s_nop 0
	v_cndmask_b32_e32 v68, v68, v69, vcc
	v_sqrt_f32_e32 v69, v68
	s_nop 0
	v_add_u32_e32 v70, -1, v69
	v_fma_f32 v71, -v70, v69, v68
	v_cmp_ge_f32_e64 s[12:13], 0, v71
	v_add_u32_e32 v71, 1, v69
	s_nop 0
	v_cndmask_b32_e64 v70, v69, v70, s[12:13]
	v_fma_f32 v69, -v71, v69, v68
	v_cmp_lt_f32_e64 s[12:13], 0, v69
	s_nop 1
	v_cndmask_b32_e64 v69, v70, v71, s[12:13]
	v_mul_f32_e32 v70, 0x37800000, v69
	v_cndmask_b32_e32 v69, v69, v70, vcc
	v_cmp_class_f32_e32 vcc, v68, v250
	s_nop 1
	v_cndmask_b32_e32 v68, v69, v68, vcc
	v_max_f32_e32 v68, 0x2b8cbccc, v68
	v_div_scale_f32 v69, s[12:13], v68, v68, v98
	v_rcp_f32_e32 v70, v69
	s_mov_b32 s12, 0x4480000
	v_fma_f32 v71, -v69, v70, 1.0
	v_fmac_f32_e32 v70, v71, v70
	v_div_scale_f32 v71, vcc, v98, v68, v98
	v_mul_f32_e32 v72, v71, v70
	v_fma_f32 v73, -v69, v72, v71
	v_fmac_f32_e32 v72, v73, v70
	v_fma_f32 v69, -v69, v72, v71
	v_div_fmas_f32 v69, v69, v70, v72
	v_div_fixup_f32 v70, v69, v68, v98
	v_add_co_u32_e32 v68, vcc, s12, v2
	s_mov_b32 s12, 0x55a0000
	s_nop 0
	v_addc_co_u32_e32 v69, vcc, 0, v3, vcc
	v_add_co_u32_e32 v2, vcc, s12, v2
	global_store_dword v[68:69], v70, off
	v_mul_f32_e32 v68, v96, v70
	v_addc_co_u32_e32 v3, vcc, 0, v3, vcc
	global_store_dword v[2:3], v68, off
	v_add_co_u32_e32 v68, vcc, s29, v0
	s_nop 1
	v_addc_co_u32_e32 v69, vcc, 0, v1, vcc
	v_mov_b32_e32 v2, v239
	v_lshlrev_b32_e32 v2, 16, v2
	v_mov_b32_e32 v68, v240
	v_mul_f32_e32 v3, 0xbfb8aa3b, v2
	v_fma_f32 v70, v2, s33, -v3
	v_rndne_f32_e32 v71, v3
	v_fmac_f32_e32 v70, 0xb2a5705f, v2
	v_sub_f32_e32 v3, v3, v71
	v_add_f32_e32 v3, v3, v70
	v_exp_f32_e32 v3, v3
	v_cvt_i32_f32_e32 v70, v71
	v_cmp_nlt_f32_e32 vcc, s72, v2
	v_ldexp_f32 v3, v3, v70
	s_nop 0
	v_cndmask_b32_e32 v3, 0, v3, vcc
	v_cmp_ngt_f32_e32 vcc, s79, v2
	v_lshlrev_b32_e32 v68, 16, v68
	v_cndmask_b32_e32 v3, v220, v3, vcc
	v_add_f32_e32 v3, 1.0, v3
	v_div_scale_f32 v70, s[12:13], v3, v3, 1.0
	v_rcp_f32_e32 v71, v70
	v_mul_f32_e32 v69, 0x3fb8aa3b, v68
	v_fma_f32 v72, -v70, v71, 1.0
	v_fmac_f32_e32 v71, v72, v71
	v_div_scale_f32 v72, vcc, 1.0, v3, 1.0
	v_mul_f32_e32 v73, v72, v71
	v_fma_f32 v74, -v70, v73, v72
	v_fmac_f32_e32 v73, v74, v71
	v_fma_f32 v70, -v70, v73, v72
	v_div_fmas_f32 v70, v70, v71, v73
	v_div_fixup_f32 v3, v70, v3, 1.0
	v_mul_f32_e32 v72, v3, v2
	v_lshlrev_b64 v[2:3], 2, v[66:67]
	v_lshl_add_u64 v[70:71], s[14:15], 0, v[2:3]
	global_store_dword v[70:71], v72, off
	v_fma_f32 v70, v68, s65, -v69
	v_rndne_f32_e32 v71, v69
	v_fmac_f32_e32 v70, 0x32a5705f, v68
	v_sub_f32_e32 v69, v69, v71
	v_add_f32_e32 v69, v69, v70
	v_exp_f32_e32 v69, v69
	v_cvt_i32_f32_e32 v70, v71
	v_cmp_ngt_f32_e32 vcc, s47, v68
	v_lshl_add_u64 v[2:3], s[16:17], 0, v[2:3]
	v_ldexp_f32 v69, v69, v70
	v_cndmask_b32_e32 v69, 0, v69, vcc
	v_cmp_nlt_f32_e32 vcc, s37, v68
	s_nop 1
	v_cndmask_b32_e32 v68, v220, v69, vcc
	v_add_f32_e32 v68, 1.0, v68
	v_div_scale_f32 v69, s[12:13], v68, v68, 1.0
	v_rcp_f32_e32 v70, v69
	s_nop 0
	v_fma_f32 v71, -v69, v70, 1.0
	v_fmac_f32_e32 v70, v71, v70
	v_div_scale_f32 v71, vcc, 1.0, v68, 1.0
	v_mul_f32_e32 v72, v71, v70
	v_fma_f32 v73, -v69, v72, v71
	v_fmac_f32_e32 v72, v73, v70
	v_fma_f32 v69, -v69, v72, v71
	v_div_fmas_f32 v69, v69, v70, v72
	v_div_fixup_f32 v68, v69, v68, 1.0
	v_mul_f32_e32 v68, v77, v68
	v_min_f32_e32 v68, 0x3f7ff972, v68
	global_store_dword v[2:3], v68, off
	s_and_saveexec_b64 s[12:13], s[6:7]
	s_cbranch_execz .LBB0_1040
	s_mov_b64 s[26:27], 0x9000
	v_mov_b32_e32 v71, 0xb000
	v_lshl_add_u64 v[68:69], v[0:1], 0, s[26:27]
	v_mov_b64_e32 v[0:1], v[222:223]
	v_mov_b64_e32 v[2:3], v[224:225]
	s_lshl_b64 s[22:23], s[22:23], 8
	v_lshlrev_b32_e32 v70, 16, v0
	v_fmac_f32_e32 v76, v95, v70
	v_and_b32_e32 v0, 0xffff0000, v0
	v_fmac_f32_e32 v76, v94, v0
	v_lshlrev_b32_e32 v0, 16, v1
	v_fmac_f32_e32 v76, v93, v0
	v_and_b32_e32 v0, 0xffff0000, v1
	v_fmac_f32_e32 v76, v92, v0
	v_lshlrev_b32_e32 v0, 16, v2
	v_fmac_f32_e32 v76, v91, v0
	v_and_b32_e32 v0, 0xffff0000, v2
	v_fmac_f32_e32 v76, v90, v0
	v_bfi_b32 v1, v237, 0, v3
	v_lshlrev_b32_e32 v0, 16, v3
	v_pk_mul_f32 v[0:1], v[64:65], v[0:1]
	s_nop 0
	v_add_f32_e32 v0, v76, v0
	v_add_f32_e32 v72, v0, v1
	v_mov_b64_e32 v[0:1], v[226:227]
	v_mov_b64_e32 v[2:3], v[228:229]
	v_bfi_b32 v71, v237, 0, v0
	v_lshlrev_b32_e32 v70, 16, v0
	v_pk_mul_f32 v[70:71], v[62:63], v[70:71]
	s_nop 0
	v_add_f32_e32 v0, v72, v70
	v_add_f32_e32 v72, v0, v71
	v_bfi_b32 v71, v237, 0, v1
	v_lshlrev_b32_e32 v70, 16, v1
	v_pk_mul_f32 v[0:1], v[60:61], v[70:71]
	s_nop 0
	v_add_f32_e32 v0, v72, v0
	v_add_f32_e32 v70, v0, v1
	v_bfi_b32 v1, v237, 0, v2
	v_lshlrev_b32_e32 v0, 16, v2
	v_pk_mul_f32 v[0:1], v[58:59], v[0:1]
	s_nop 0
	v_add_f32_e32 v0, v70, v0
	v_add_f32_e32 v2, v0, v1
	v_bfi_b32 v1, v237, 0, v3
	v_lshlrev_b32_e32 v0, 16, v3
	v_pk_mul_f32 v[0:1], v[56:57], v[0:1]
	s_nop 0
	v_add_f32_e32 v0, v2, v0
	v_add_f32_e32 v70, v0, v1
	v_add_co_u32_e32 v0, vcc, s74, v68
	s_nop 1
	v_addc_co_u32_e32 v1, vcc, 0, v69, vcc
	v_mov_b32_e32 v0, v241
	v_mov_b32_e32 v1, s23
	v_lshlrev_b32_e32 v0, 16, v0
	v_mul_f32_e32 v68, 0x3e000000, v0
	v_subrev_co_u32_e32 v0, vcc, s22, v66
	s_nop 1
	v_subb_co_u32_e32 v1, vcc, v67, v1, vcc
	v_lshlrev_b64 v[0:1], 2, v[0:1]
	v_lshl_add_u64 v[2:3], s[18:19], 0, v[0:1]
	global_store_dword v[2:3], v68, off
	v_mul_f32_e64 v3, |v70|, s33
	v_fma_f32 v66, |v70|, s33, -v3
	v_rndne_f32_e32 v67, v3
	v_fma_f32 v66, |v70|, s71, v66
	v_sub_f32_e32 v3, v3, v67
	v_add_f32_e32 v3, v3, v66
	v_exp_f32_e32 v3, v3
	v_cvt_i32_f32_e32 v66, v67
	v_cmp_ngt_f32_e64 vcc, |v70|, s72
	v_min_f32_e32 v2, 0, v70
	v_lshl_add_u64 v[0:1], s[20:21], 0, v[0:1]
	v_ldexp_f32 v3, v3, v66
	v_cndmask_b32_e32 v3, 0, v3, vcc
	v_cmp_nlt_f32_e64 vcc, |v70|, s79
	s_nop 1
	v_cndmask_b32_e32 v3, v220, v3, vcc
	v_add_f32_e32 v68, 1.0, v3
	v_add_f32_e32 v66, -1.0, v68
	v_sub_f32_e32 v67, v66, v68
	v_add_f32_e32 v67, 1.0, v67
	v_sub_f32_e32 v66, v3, v66
	v_add_f32_e32 v69, v66, v67
	v_frexp_mant_f32_e32 v66, v68
	v_cmp_gt_f32_e32 vcc, s76, v66
	v_cvt_f64_f32_e32 v[66:67], v68
	v_frexp_exp_i32_f64_e32 v66, v[66:67]
	v_subbrev_co_u32_e32 v66, vcc, 0, v66, vcc
	v_sub_u32_e32 v67, 0, v66
	v_ldexp_f32 v68, v68, v67
	v_ldexp_f32 v67, v69, v67
	v_add_f32_e32 v69, -1.0, v68
	v_add_f32_e32 v70, 1.0, v69
	v_sub_f32_e32 v70, v68, v70
	v_add_f32_e32 v70, v67, v70
	v_add_f32_e32 v71, v69, v70
	v_sub_f32_e32 v69, v69, v71
	v_add_f32_e32 v69, v70, v69
	v_add_f32_e32 v70, 1.0, v68
	v_add_f32_e32 v72, -1.0, v70
	v_sub_f32_e32 v68, v68, v72
	v_add_f32_e32 v67, v67, v68
	v_add_f32_e32 v68, v70, v67
	v_sub_f32_e32 v70, v70, v68
	v_add_f32_e32 v67, v67, v70
	v_rcp_f32_e32 v70, v68
	v_cvt_f32_i32_e32 v66, v66
	v_cmp_neq_f32_e32 vcc, s49, v3
	v_mul_f32_e32 v72, v71, v70
	v_mul_f32_e32 v73, v68, v72
	v_fma_f32 v74, v72, v68, -v73
	v_fmac_f32_e32 v74, v72, v67
	v_add_f32_e32 v75, v73, v74
	v_sub_f32_e32 v76, v71, v75
	v_sub_f32_e32 v71, v71, v76
	v_sub_f32_e32 v73, v75, v73
	v_sub_f32_e32 v71, v71, v75
	v_add_f32_e32 v69, v69, v71
	v_sub_f32_e32 v71, v73, v74
	v_add_f32_e32 v69, v71, v69
	v_add_f32_e32 v71, v76, v69
	v_mul_f32_e32 v73, v70, v71
	v_mul_f32_e32 v74, v68, v73
	v_fma_f32 v68, v73, v68, -v74
	v_fmac_f32_e32 v68, v73, v67
	v_sub_f32_e32 v67, v76, v71
	v_add_f32_e32 v67, v69, v67
	v_add_f32_e32 v69, v74, v68
	v_sub_f32_e32 v75, v71, v69
	v_sub_f32_e32 v71, v71, v75
	v_sub_f32_e32 v74, v69, v74
	v_sub_f32_e32 v69, v71, v69
	v_add_f32_e32 v67, v67, v69
	v_sub_f32_e32 v68, v74, v68
	v_add_f32_e32 v67, v68, v67
	v_add_f32_e32 v68, v72, v73
	v_add_f32_e32 v67, v75, v67
	v_sub_f32_e32 v69, v68, v72
	v_mul_f32_e32 v67, v70, v67
	v_sub_f32_e32 v69, v73, v69
	v_add_f32_e32 v67, v69, v67
	v_mul_f32_e32 v72, 0x3f317218, v66
	v_add_f32_e32 v69, v68, v67
	v_fma_f32 v73, v66, s77, -v72
	v_mul_f32_e32 v70, v69, v69
	v_fmac_f32_e32 v73, 0xb102e308, v66
	v_sub_f32_e32 v66, v69, v68
	v_fmamk_f32 v71, v70, 0x3e9b6dac, v230
	v_sub_f32_e32 v66, v67, v66
	v_add_f32_e32 v67, v72, v73
	v_fmaak_f32 v71, v70, v71, 0x3f2aaada
	v_sub_f32_e32 v68, v67, v72
	v_ldexp_f32 v72, v69, 1
	v_mul_f32_e32 v69, v69, v70
	v_mul_f32_e32 v69, v69, v71
	v_add_f32_e32 v70, v72, v69
	v_sub_f32_e32 v71, v70, v72
	v_ldexp_f32 v66, v66, 1
	v_sub_f32_e32 v69, v69, v71
	v_add_f32_e32 v66, v66, v69
	v_add_f32_e32 v69, v70, v66
	v_sub_f32_e32 v70, v69, v70
	v_sub_f32_e32 v66, v66, v70
	v_add_f32_e32 v70, v67, v69
	v_sub_f32_e32 v71, v70, v67
	v_sub_f32_e32 v72, v70, v71
	v_sub_f32_e32 v68, v73, v68
	v_sub_f32_e32 v67, v67, v72
	v_sub_f32_e32 v69, v69, v71
	v_add_f32_e32 v67, v69, v67
	v_add_f32_e32 v69, v68, v66
	v_sub_f32_e32 v71, v69, v68
	v_sub_f32_e32 v72, v69, v71
	v_sub_f32_e32 v68, v68, v72
	v_sub_f32_e32 v66, v66, v71
	v_add_f32_e32 v67, v69, v67
	v_add_f32_e32 v66, v66, v68
	v_add_f32_e32 v68, v70, v67
	v_sub_f32_e32 v69, v68, v70
	v_sub_f32_e32 v67, v67, v69
	v_add_f32_e32 v66, v66, v67
	v_add_f32_e32 v66, v68, v66
	v_cndmask_b32_e32 v66, v220, v66, vcc
	v_cmp_lt_f32_e64 vcc, |v3|, s78
	s_nop 1
	v_cndmask_b32_e32 v3, v66, v3, vcc
	v_sub_f32_e32 v2, v2, v3
	v_mul_f32_e32 v2, 0x3d800000, v2
	v_mul_f32_e32 v3, 0x3fb8aa3b, v2
	v_fma_f32 v66, v2, s65, -v3
	v_rndne_f32_e32 v67, v3
	v_fmac_f32_e32 v66, 0x32a5705f, v2
	v_sub_f32_e32 v3, v3, v67
	v_add_f32_e32 v3, v3, v66
	v_exp_f32_e32 v3, v3
	v_cvt_i32_f32_e32 v66, v67
	v_cmp_ngt_f32_e32 vcc, s47, v2
	v_ldexp_f32 v3, v3, v66
	s_nop 0
	v_cndmask_b32_e32 v3, 0, v3, vcc
	v_cmp_nlt_f32_e32 vcc, s37, v2
	s_nop 1
	v_cndmask_b32_e32 v2, v220, v3, vcc
	global_store_dword v[0:1], v2, off
	s_branch .LBB0_1040
